# K loop: s_setprio 1 issued before the pre-compute barrier (so the wake-up into the MFMA segment is already prioritised), s_setprio 0 after the post-compute barrier
# speedup vs baseline: 1.0086x; 1.0012x over previous
; #define PG8_STAGE(bufoff, gbase, voff) do { _Pragma("unroll") for (int _i = 0; _i < 2; ++_i) \
;         __builtin_amdgcn_global_load_lds((const unsigned*)((const char*)(gbase) + (voff)[_i]), (PG8_LAS unsigned*)(lds + (bufoff) + ldsw + _i * 8192), 16, 0, 0); } while (0)
; #define PG8_LDA(dst, b, h) do { _Pragma("unroll") for (int m = 0; m < 4; ++m) _Pragma("unroll") for (int k = 0; k < 2; ++k) dst[m][k] = *(const PG8_LAS bf16x8*)(lds + PG8_SA(b, h) + aoff + m * 2048 + k * 1024); } while (0)
; #define PG8_LDB(dst, b, h) do { _Pragma("unroll") for (int n = 0; n < 2; ++n) _Pragma("unroll") for (int k = 0; k < 2; ++k) dst[n][k] = *(const PG8_LAS bf16x8*)(lds + PG8_SB(b, h) + boff + n * 2048 + k * 1024); } while (0)
; #define PG8_MMA(ai, bj, At, Bt) do { __builtin_amdgcn_s_setprio(1); _Pragma("unroll") for (int m = 0; m < 4; ++m) _Pragma("unroll") for (int n = 0; n < 2; ++n) _Pragma("unroll") for (int k = 0; k < 2; ++k) \
;         acc[ai][bj][m][n] = __builtin_amdgcn_mfma_f32_16x16x32_bf16(Bt[n][k], At[m][k], acc[ai][bj][m][n], 0, 0, 0); __builtin_amdgcn_s_setprio(0); } while (0)
; #define PG8_WAIT_V(n) asm volatile("s_waitcnt vmcnt(" #n ")" ::: "memory")
; #define PG8_BAR __builtin_amdgcn_s_barrier()
; template <class Epi, class Sched, bool ALIGN_EPI = false, bool SP2 = false>
; __device__ __forceinline__ void gemm_phase(PG8_LAS unsigned char* lds, const Gemm g, const Sched& S, const Epi& E) {
;     ...
;         for (int t = 0; t < nt; t += 2) {
;             const bool last = (t == nt - 2);
;             const char* a1 = cA + (size_t)(t + 1) * kstep;
;             const char* a2 = last ? nA : cA + (size_t)(t + 2) * kstep; const char* b2 = last ? nB : cB + (size_t)(t + 2) * kstep;
;             const char* a3 = a2 + kstep; const char* b3 = b2 + kstep;
;             if (last && has_next) S.a_ready(nxt);
;             if constexpr (SP2) {
;             PG8_LDB(B0, 0, 0); PG8_LDB(B1, 0, 1); PG8_SCHED; PG8_LDA(At, 0, 0); PG8_STAGE(PG8_SA(1, 1), a1 + hstep, voffA);
;             PG8_WAIT_V(8); PG8_WAIT_L(0); PG8_BAR; PG8_MMA(0, 0, At, B0); PG8_MMA(0, 1, At, B1); PG8_BAR; PG8_SCHED;
;             PG8_LDA(At, 0, 1); PG8_STAGE(PG8_SB(0, 0), b2, voffB); PG8_STAGE(PG8_SB(0, 1), b2 + hstep, voffB); PG8_STAGE(PG8_SA(0, 0), a2, voffA);
;             PG8_WAIT_V(8); PG8_WAIT_L(0); PG8_BAR; PG8_MMA(1, 0, At, B0); PG8_MMA(1, 1, At, B1); PG8_BAR; PG8_SCHED;
.LBB0_321:
	s_add_u32 s12, s16, 0x80
	s_addc_u32 s13, s17, 0
	s_add_u32 s16, s14, 0x100
	s_addc_u32 s17, s15, 0
	s_mov_b32 s14, 0
	s_nop 0
	s_nop 0
	s_waitcnt lgkmcnt(0)
	s_add_i32 s42, s14, 2
	s_add_u32 s43, s12, 0x80
	s_addc_u32 s15, s13, 0
	s_add_i32 s75, 0, 0x10000
	s_cmp_eq_u32 s25, s14
	s_cselect_b32 s15, s55, s15
	s_cselect_b32 s14, s54, s43
	s_cselect_b32 vcc_hi, s65, s17
	s_cselect_b32 vcc_lo, s64, s16
	s_add_i32 s43, 0, 0x14000
	v_add_u32_e32 v142, s75, v199
	v_add_u32_e32 v178, s43, v199
	ds_read_b128 v[130:133], v142
	ds_read_b128 v[134:137], v142 offset:1024
	ds_read_b128 v[138:141], v142 offset:2048
	ds_read_b128 v[142:145], v142 offset:3072
	ds_read_b128 v[170:173], v178
	ds_read_b128 v[174:177], v178 offset:1024
	ds_read_b128 v[202:205], v178 offset:2048
	ds_read_b128 v[206:209], v178 offset:3072
	v_lshl_add_u64 v[178:179], s[12:13], 0, v[166:167]
	s_add_i32 m0, s56, 0xc000
	ds_read_b128 v[210:213], v201
	ds_read_b128 v[214:217], v201 offset:1024
	ds_read_b128 v[218:221], v201 offset:2048
	ds_read_b128 v[222:225], v201 offset:3072
	ds_read_b128 v[226:229], v201 offset:4096
	ds_read_b128 v[230:233], v201 offset:5120
	ds_read_b128 v[234:237], v201 offset:6144
	ds_read_b128 v[238:241], v201 offset:7168
	global_load_lds_dwordx4 v[178:179], off
	v_lshl_add_u64 v[178:179], s[12:13], 0, v[168:169]
	s_add_i32 m0, s56, 0xe000
	s_nop 0
	global_load_lds_dwordx4 v[178:179], off
	s_waitcnt vmcnt(8)
	s_waitcnt lgkmcnt(0)
	s_setprio 1
	s_barrier
	v_mfma_f32_16x16x32_bf16 v[126:129], v[130:133], v[210:213], 0
	v_mfma_f32_16x16x32_bf16 v[126:129], v[134:137], v[214:217], v[126:129]
	v_mfma_f32_16x16x32_bf16 v[122:125], v[138:141], v[210:213], 0
	v_mfma_f32_16x16x32_bf16 v[122:125], v[142:145], v[214:217], v[122:125]
	v_mfma_f32_16x16x32_bf16 v[110:113], v[130:133], v[218:221], 0
	v_mfma_f32_16x16x32_bf16 v[110:113], v[134:137], v[222:225], v[110:113]
	v_mfma_f32_16x16x32_bf16 v[106:109], v[138:141], v[218:221], 0
	v_mfma_f32_16x16x32_bf16 v[106:109], v[142:145], v[222:225], v[106:109]
	v_mfma_f32_16x16x32_bf16 v[94:97], v[130:133], v[226:229], 0
	v_mfma_f32_16x16x32_bf16 v[94:97], v[134:137], v[230:233], v[94:97]
	v_mfma_f32_16x16x32_bf16 v[90:93], v[138:141], v[226:229], 0
	v_mfma_f32_16x16x32_bf16 v[90:93], v[142:145], v[230:233], v[90:93]
	v_mfma_f32_16x16x32_bf16 v[78:81], v[130:133], v[234:237], 0
	v_mfma_f32_16x16x32_bf16 v[78:81], v[134:137], v[238:241], v[78:81]
	v_mfma_f32_16x16x32_bf16 v[74:77], v[138:141], v[234:237], 0
	v_mfma_f32_16x16x32_bf16 v[74:77], v[142:145], v[238:241], v[74:77]
	v_mfma_f32_16x16x32_bf16 v[118:121], v[170:173], v[210:213], 0
	v_mfma_f32_16x16x32_bf16 v[118:121], v[174:177], v[214:217], v[118:121]
	v_mfma_f32_16x16x32_bf16 v[114:117], v[202:205], v[210:213], 0
	v_mfma_f32_16x16x32_bf16 v[114:117], v[206:209], v[214:217], v[114:117]
	v_mfma_f32_16x16x32_bf16 v[102:105], v[170:173], v[218:221], 0
	v_mfma_f32_16x16x32_bf16 v[102:105], v[174:177], v[222:225], v[102:105]
	v_mfma_f32_16x16x32_bf16 v[98:101], v[202:205], v[218:221], 0
	v_mfma_f32_16x16x32_bf16 v[98:101], v[206:209], v[222:225], v[98:101]
	v_mfma_f32_16x16x32_bf16 v[86:89], v[170:173], v[226:229], 0
	v_mfma_f32_16x16x32_bf16 v[86:89], v[174:177], v[230:233], v[86:89]
	v_mfma_f32_16x16x32_bf16 v[82:85], v[202:205], v[226:229], 0
	v_mfma_f32_16x16x32_bf16 v[82:85], v[206:209], v[230:233], v[82:85]
	v_mfma_f32_16x16x32_bf16 v[70:73], v[170:173], v[234:237], 0
	v_mfma_f32_16x16x32_bf16 v[70:73], v[174:177], v[238:241], v[70:73]
	v_mfma_f32_16x16x32_bf16 v[66:69], v[202:205], v[234:237], 0
	v_mfma_f32_16x16x32_bf16 v[66:69], v[206:209], v[238:241], v[66:69]
	s_barrier
	s_setprio 0
	s_add_i32 s75, s75, s23
	v_lshl_add_u64 v[178:179], vcc, 0, v[0:1]
	s_mov_b32 m0, s75
	ds_read_b128 v[210:213], v201 offset:16384
	ds_read_b128 v[214:217], v201 offset:17408
	ds_read_b128 v[218:221], v201 offset:18432
	ds_read_b128 v[222:225], v201 offset:19456
	ds_read_b128 v[226:229], v201 offset:20480
	ds_read_b128 v[230:233], v201 offset:21504
	ds_read_b128 v[234:237], v201 offset:22528
	ds_read_b128 v[238:241], v201 offset:23552
	global_load_lds_dwordx4 v[178:179], off
	s_add_i32 m0, s75, 0x2000
	v_lshl_add_u64 v[242:243], vcc, 0, v[162:163]
	s_add_u32 vcc_lo, vcc_lo, s84
	s_addc_u32 vcc_hi, vcc_hi, 0
	s_add_i32 s43, s43, s23
	global_load_lds_dwordx4 v[242:243], off
	v_lshl_add_u64 v[244:245], vcc, 0, v[0:1]
	s_mov_b32 m0, s43
	v_lshl_add_u64 v[246:247], vcc, 0, v[162:163]
	global_load_lds_dwordx4 v[244:245], off
	s_add_i32 m0, s43, 0x2000
	v_lshl_add_u64 v[248:249], s[14:15], 0, v[158:159]
	global_load_lds_dwordx4 v[246:247], off
	s_mov_b32 m0, s56
	v_lshl_add_u64 v[250:251], s[14:15], 0, v[160:161]
	global_load_lds_dwordx4 v[248:249], off
	s_mov_b32 m0, s82
	s_nop 0
	global_load_lds_dwordx4 v[250:251], off
	s_waitcnt vmcnt(8)
	s_waitcnt lgkmcnt(0)
	s_setprio 1
	s_barrier
; #define PG8_STAGE(bufoff, gbase, voff) do { _Pragma("unroll") for (int _i = 0; _i < 2; ++_i) \
;         __builtin_amdgcn_global_load_lds((const unsigned*)((const char*)(gbase) + (voff)[_i]), (PG8_LAS unsigned*)(lds + (bufoff) + ldsw + _i * 8192), 16, 0, 0); } while (0)
; #define PG8_LDA(dst, b, h) do { _Pragma("unroll") for (int m = 0; m < 4; ++m) _Pragma("unroll") for (int k = 0; k < 2; ++k) dst[m][k] = *(const PG8_LAS bf16x8*)(lds + PG8_SA(b, h) + aoff + m * 2048 + k * 1024); } while (0)
; #define PG8_LDB(dst, b, h) do { _Pragma("unroll") for (int n = 0; n < 2; ++n) _Pragma("unroll") for (int k = 0; k < 2; ++k) dst[n][k] = *(const PG8_LAS bf16x8*)(lds + PG8_SB(b, h) + boff + n * 2048 + k * 1024); } while (0)
; #define PG8_MMA(ai, bj, At, Bt) do { __builtin_amdgcn_s_setprio(1); _Pragma("unroll") for (int m = 0; m < 4; ++m) _Pragma("unroll") for (int n = 0; n < 2; ++n) _Pragma("unroll") for (int k = 0; k < 2; ++k) \
;         acc[ai][bj][m][n] = __builtin_amdgcn_mfma_f32_16x16x32_bf16(Bt[n][k], At[m][k], acc[ai][bj][m][n], 0, 0, 0); __builtin_amdgcn_s_setprio(0); } while (0)
; #define PG8_WAIT_V(n) asm volatile("s_waitcnt vmcnt(" #n ")" ::: "memory")
; #define PG8_WAIT_L(n) asm volatile("s_waitcnt lgkmcnt(" #n ")" ::: "memory")
; #define PG8_BAR __builtin_amdgcn_s_barrier()
; #define PG8_SCHED __builtin_amdgcn_sched_barrier(0)
; template <class Epi, class Sched, bool ALIGN_EPI = false, bool SP2 = false>
; __device__ __forceinline__ void gemm_phase(PG8_LAS unsigned char* lds, const Gemm g, const Sched& S, const Epi& E) {
;     ...
;             PG8_WAIT_V(8); PG8_WAIT_L(0); PG8_BAR; PG8_MMA(1, 0, At, B0); PG8_MMA(1, 1, At, B1); PG8_BAR; PG8_SCHED;
;             PG8_LDB(B0, 1, 0); PG8_LDB(B1, 1, 1); PG8_SCHED; PG8_LDA(At, 1, 0); PG8_STAGE(PG8_SA(0, 1), a2 + hstep, voffA);
;             PG8_WAIT_V(8); PG8_WAIT_L(0); PG8_BAR; PG8_MMA(0, 0, At, B0); PG8_MMA(0, 1, At, B1); PG8_BAR; PG8_SCHED;
	v_mfma_f32_16x16x32_bf16 v[62:65], v[130:133], v[210:213], 0
	v_mfma_f32_16x16x32_bf16 v[62:65], v[134:137], v[214:217], v[62:65]
	v_mfma_f32_16x16x32_bf16 v[58:61], v[138:141], v[210:213], 0
	v_mfma_f32_16x16x32_bf16 v[58:61], v[142:145], v[214:217], v[58:61]
	v_mfma_f32_16x16x32_bf16 v[46:49], v[130:133], v[218:221], 0
	v_mfma_f32_16x16x32_bf16 v[46:49], v[134:137], v[222:225], v[46:49]
	v_mfma_f32_16x16x32_bf16 v[42:45], v[138:141], v[218:221], 0
	v_mfma_f32_16x16x32_bf16 v[42:45], v[142:145], v[222:225], v[42:45]
	v_mfma_f32_16x16x32_bf16 v[30:33], v[130:133], v[226:229], 0
	v_mfma_f32_16x16x32_bf16 v[30:33], v[134:137], v[230:233], v[30:33]
	v_mfma_f32_16x16x32_bf16 v[26:29], v[138:141], v[226:229], 0
	v_mfma_f32_16x16x32_bf16 v[26:29], v[142:145], v[230:233], v[26:29]
	v_mfma_f32_16x16x32_bf16 v[14:17], v[130:133], v[234:237], 0
	v_mfma_f32_16x16x32_bf16 v[14:17], v[134:137], v[238:241], v[14:17]
	v_mfma_f32_16x16x32_bf16 v[10:13], v[138:141], v[234:237], 0
	v_mfma_f32_16x16x32_bf16 v[10:13], v[142:145], v[238:241], v[10:13]
	v_mfma_f32_16x16x32_bf16 v[54:57], v[170:173], v[210:213], 0
	v_mfma_f32_16x16x32_bf16 v[54:57], v[174:177], v[214:217], v[54:57]
	v_mfma_f32_16x16x32_bf16 v[50:53], v[202:205], v[210:213], 0
	v_mfma_f32_16x16x32_bf16 v[50:53], v[206:209], v[214:217], v[50:53]
	v_mfma_f32_16x16x32_bf16 v[38:41], v[170:173], v[218:221], 0
	v_mfma_f32_16x16x32_bf16 v[38:41], v[174:177], v[222:225], v[38:41]
	v_mfma_f32_16x16x32_bf16 v[34:37], v[202:205], v[218:221], 0
	v_mfma_f32_16x16x32_bf16 v[34:37], v[206:209], v[222:225], v[34:37]
	v_mfma_f32_16x16x32_bf16 v[22:25], v[170:173], v[226:229], 0
	v_mfma_f32_16x16x32_bf16 v[22:25], v[174:177], v[230:233], v[22:25]
	v_mfma_f32_16x16x32_bf16 v[18:21], v[202:205], v[226:229], 0
	v_mfma_f32_16x16x32_bf16 v[18:21], v[206:209], v[230:233], v[18:21]
	v_mfma_f32_16x16x32_bf16 v[6:9], v[170:173], v[234:237], 0
	v_mfma_f32_16x16x32_bf16 v[6:9], v[174:177], v[238:241], v[6:9]
	v_mfma_f32_16x16x32_bf16 v[2:5], v[202:205], v[234:237], 0
	v_mfma_f32_16x16x32_bf16 v[2:5], v[206:209], v[238:241], v[2:5]
	s_barrier
	s_setprio 0
	s_add_i32 s43, 0, 0x18000
	s_add_i32 s75, 0, 0x1c000
	v_add_u32_e32 v142, s43, v199
	v_add_u32_e32 v206, s75, v199
	ds_read_b128 v[130:133], v142
	ds_read_b128 v[134:137], v142 offset:1024
	ds_read_b128 v[138:141], v142 offset:2048
	ds_read_b128 v[142:145], v142 offset:3072
	ds_read_b128 v[170:173], v206
	ds_read_b128 v[174:177], v206 offset:1024
	ds_read_b128 v[202:205], v206 offset:2048
	ds_read_b128 v[206:209], v206 offset:3072
	s_add_u32 s14, s14, s84
	s_addc_u32 s15, s15, 0
	s_mov_b32 m0, s83
	v_lshl_add_u64 v[252:253], s[14:15], 0, v[158:159]
	ds_read_b128 v[210:213], v201 offset:32768
	ds_read_b128 v[214:217], v201 offset:33792
	ds_read_b128 v[218:221], v201 offset:34816
	ds_read_b128 v[222:225], v201 offset:35840
	ds_read_b128 v[226:229], v201 offset:36864
	ds_read_b128 v[230:233], v201 offset:37888
	ds_read_b128 v[234:237], v201 offset:38912
	ds_read_b128 v[238:241], v201 offset:39936
	global_load_lds_dwordx4 v[252:253], off
	v_lshl_add_u64 v[252:253], s[14:15], 0, v[160:161]
	s_mov_b32 m0, s24
	s_nop 0
	global_load_lds_dwordx4 v[252:253], off
	s_waitcnt vmcnt(8)
	s_waitcnt lgkmcnt(0)
	s_setprio 1
	s_barrier
	v_mfma_f32_16x16x32_bf16 v[126:129], v[130:133], v[210:213], v[126:129]
	v_mfma_f32_16x16x32_bf16 v[126:129], v[134:137], v[214:217], v[126:129]
	v_mfma_f32_16x16x32_bf16 v[122:125], v[138:141], v[210:213], v[122:125]
	v_mfma_f32_16x16x32_bf16 v[122:125], v[142:145], v[214:217], v[122:125]
	v_mfma_f32_16x16x32_bf16 v[110:113], v[130:133], v[218:221], v[110:113]
	v_mfma_f32_16x16x32_bf16 v[110:113], v[134:137], v[222:225], v[110:113]
	v_mfma_f32_16x16x32_bf16 v[106:109], v[138:141], v[218:221], v[106:109]
	v_mfma_f32_16x16x32_bf16 v[106:109], v[142:145], v[222:225], v[106:109]
	v_mfma_f32_16x16x32_bf16 v[94:97], v[130:133], v[226:229], v[94:97]
	v_mfma_f32_16x16x32_bf16 v[94:97], v[134:137], v[230:233], v[94:97]
	v_mfma_f32_16x16x32_bf16 v[90:93], v[138:141], v[226:229], v[90:93]
	v_mfma_f32_16x16x32_bf16 v[90:93], v[142:145], v[230:233], v[90:93]
	v_mfma_f32_16x16x32_bf16 v[78:81], v[130:133], v[234:237], v[78:81]
	v_mfma_f32_16x16x32_bf16 v[78:81], v[134:137], v[238:241], v[78:81]
	v_mfma_f32_16x16x32_bf16 v[74:77], v[138:141], v[234:237], v[74:77]
	v_mfma_f32_16x16x32_bf16 v[74:77], v[142:145], v[238:241], v[74:77]
	v_mfma_f32_16x16x32_bf16 v[118:121], v[170:173], v[210:213], v[118:121]
	v_mfma_f32_16x16x32_bf16 v[118:121], v[174:177], v[214:217], v[118:121]
	v_mfma_f32_16x16x32_bf16 v[114:117], v[202:205], v[210:213], v[114:117]
	v_mfma_f32_16x16x32_bf16 v[114:117], v[206:209], v[214:217], v[114:117]
	v_mfma_f32_16x16x32_bf16 v[102:105], v[170:173], v[218:221], v[102:105]
	v_mfma_f32_16x16x32_bf16 v[102:105], v[174:177], v[222:225], v[102:105]
	v_mfma_f32_16x16x32_bf16 v[98:101], v[202:205], v[218:221], v[98:101]
	v_mfma_f32_16x16x32_bf16 v[98:101], v[206:209], v[222:225], v[98:101]
	v_mfma_f32_16x16x32_bf16 v[86:89], v[170:173], v[226:229], v[86:89]
	v_mfma_f32_16x16x32_bf16 v[86:89], v[174:177], v[230:233], v[86:89]
	v_mfma_f32_16x16x32_bf16 v[82:85], v[202:205], v[226:229], v[82:85]
	v_mfma_f32_16x16x32_bf16 v[82:85], v[206:209], v[230:233], v[82:85]
	v_mfma_f32_16x16x32_bf16 v[70:73], v[170:173], v[234:237], v[70:73]
	v_mfma_f32_16x16x32_bf16 v[70:73], v[174:177], v[238:241], v[70:73]
	v_mfma_f32_16x16x32_bf16 v[66:69], v[202:205], v[234:237], v[66:69]
	v_mfma_f32_16x16x32_bf16 v[66:69], v[206:209], v[238:241], v[66:69]
	s_barrier
; #define PG8_STAGE(bufoff, gbase, voff) do { _Pragma("unroll") for (int _i = 0; _i < 2; ++_i) \
;         __builtin_amdgcn_global_load_lds((const unsigned*)((const char*)(gbase) + (voff)[_i]), (PG8_LAS unsigned*)(lds + (bufoff) + ldsw + _i * 8192), 16, 0, 0); } while (0)
; #define PG8_LDA(dst, b, h) do { _Pragma("unroll") for (int m = 0; m < 4; ++m) _Pragma("unroll") for (int k = 0; k < 2; ++k) dst[m][k] = *(const PG8_LAS bf16x8*)(lds + PG8_SA(b, h) + aoff + m * 2048 + k * 1024); } while (0)
; #define PG8_LDB(dst, b, h) do { _Pragma("unroll") for (int n = 0; n < 2; ++n) _Pragma("unroll") for (int k = 0; k < 2; ++k) dst[n][k] = *(const PG8_LAS bf16x8*)(lds + PG8_SB(b, h) + boff + n * 2048 + k * 1024); } while (0)
; #define PG8_MMA(ai, bj, At, Bt) do { __builtin_amdgcn_s_setprio(1); _Pragma("unroll") for (int m = 0; m < 4; ++m) _Pragma("unroll") for (int n = 0; n < 2; ++n) _Pragma("unroll") for (int k = 0; k < 2; ++k) \
;         acc[ai][bj][m][n] = __builtin_amdgcn_mfma_f32_16x16x32_bf16(Bt[n][k], At[m][k], acc[ai][bj][m][n], 0, 0, 0); __builtin_amdgcn_s_setprio(0); } while (0)
; #define PG8_WAIT_V(n) asm volatile("s_waitcnt vmcnt(" #n ")" ::: "memory")
; #define PG8_WAIT_L(n) asm volatile("s_waitcnt lgkmcnt(" #n ")" ::: "memory")
; #define PG8_BAR __builtin_amdgcn_s_barrier()
; #define PG8_SCHED __builtin_amdgcn_sched_barrier(0)
; template <class Epi, class Sched, bool ALIGN_EPI = false, bool SP2 = false>
; __device__ __forceinline__ void gemm_phase(PG8_LAS unsigned char* lds, const Gemm g, const Sched& S, const Epi& E) {
;     ...
;         for (int t = 0; t < nt; t += 2) {
;             const bool last = (t == nt - 2);
;             const char* a1 = cA + (size_t)(t + 1) * kstep;
;             const char* a2 = last ? nA : cA + (size_t)(t + 2) * kstep; const char* b2 = last ? nB : cB + (size_t)(t + 2) * kstep;
;             const char* a3 = a2 + kstep; const char* b3 = b2 + kstep;
;             if (last && has_next) S.a_ready(nxt);
;             if constexpr (SP2) {
;             PG8_LDB(B0, 0, 0); PG8_LDB(B1, 0, 1); PG8_SCHED; PG8_LDA(At, 0, 0); PG8_STAGE(PG8_SA(1, 1), a1 + hstep, voffA);
;     ...
;             PG8_LDA(At, 1, 1); PG8_STAGE(PG8_SB(1, 0), b3, voffB); PG8_STAGE(PG8_SB(1, 1), b3 + hstep, voffB); PG8_STAGE(PG8_SA(1, 0), a3, voffA);
;             PG8_WAIT_V(8); PG8_WAIT_L(0); PG8_BAR; PG8_MMA(1, 0, At, B0); PG8_MMA(1, 1, At, B1); PG8_BAR; PG8_SCHED;
	s_setprio 0
	s_add_i32 s14, s43, s23
	v_lshl_add_u64 v[178:179], v[178:179], 0, s[94:95]
	s_mov_b32 m0, s14
	ds_read_b128 v[210:213], v201 offset:49152
	ds_read_b128 v[214:217], v201 offset:50176
	ds_read_b128 v[218:221], v201 offset:51200
	ds_read_b128 v[222:225], v201 offset:52224
	ds_read_b128 v[226:229], v201 offset:53248
	ds_read_b128 v[230:233], v201 offset:54272
	ds_read_b128 v[234:237], v201 offset:55296
	ds_read_b128 v[238:241], v201 offset:56320
	global_load_lds_dwordx4 v[178:179], off
	v_lshl_add_u64 v[178:179], v[242:243], 0, s[94:95]
	s_add_i32 m0, s14, 0x2000
	s_add_i32 s14, s75, s23
	global_load_lds_dwordx4 v[178:179], off
	v_lshl_add_u64 v[178:179], v[244:245], 0, s[94:95]
	s_mov_b32 m0, s14
	s_nop 0
	global_load_lds_dwordx4 v[178:179], off
	v_lshl_add_u64 v[178:179], v[246:247], 0, s[94:95]
	s_add_i32 m0, s14, 0x2000
	s_nop 0
	global_load_lds_dwordx4 v[178:179], off
	v_lshl_add_u64 v[178:179], v[248:249], 0, s[94:95]
	s_mov_b32 m0, s63
	s_nop 0
	global_load_lds_dwordx4 v[178:179], off
	v_lshl_add_u64 v[178:179], v[250:251], 0, s[94:95]
	s_mov_b32 m0, s70
	s_nop 0
	global_load_lds_dwordx4 v[178:179], off
	s_waitcnt vmcnt(8)
	s_waitcnt lgkmcnt(0)
	s_setprio 1
	s_barrier
	v_mfma_f32_16x16x32_bf16 v[62:65], v[130:133], v[210:213], v[62:65]
	v_mfma_f32_16x16x32_bf16 v[62:65], v[134:137], v[214:217], v[62:65]
	v_mfma_f32_16x16x32_bf16 v[58:61], v[138:141], v[210:213], v[58:61]
	v_mfma_f32_16x16x32_bf16 v[58:61], v[142:145], v[214:217], v[58:61]
	v_mfma_f32_16x16x32_bf16 v[46:49], v[130:133], v[218:221], v[46:49]
	v_mfma_f32_16x16x32_bf16 v[46:49], v[134:137], v[222:225], v[46:49]
	v_mfma_f32_16x16x32_bf16 v[42:45], v[138:141], v[218:221], v[42:45]
	v_mfma_f32_16x16x32_bf16 v[42:45], v[142:145], v[222:225], v[42:45]
	v_mfma_f32_16x16x32_bf16 v[30:33], v[130:133], v[226:229], v[30:33]
	v_mfma_f32_16x16x32_bf16 v[30:33], v[134:137], v[230:233], v[30:33]
	v_mfma_f32_16x16x32_bf16 v[26:29], v[138:141], v[226:229], v[26:29]
	v_mfma_f32_16x16x32_bf16 v[26:29], v[142:145], v[230:233], v[26:29]
	v_mfma_f32_16x16x32_bf16 v[14:17], v[130:133], v[234:237], v[14:17]
	v_mfma_f32_16x16x32_bf16 v[14:17], v[134:137], v[238:241], v[14:17]
	v_mfma_f32_16x16x32_bf16 v[10:13], v[138:141], v[234:237], v[10:13]
	v_mfma_f32_16x16x32_bf16 v[10:13], v[142:145], v[238:241], v[10:13]
	v_mfma_f32_16x16x32_bf16 v[54:57], v[170:173], v[210:213], v[54:57]
	v_mfma_f32_16x16x32_bf16 v[54:57], v[174:177], v[214:217], v[54:57]
	v_mfma_f32_16x16x32_bf16 v[50:53], v[202:205], v[210:213], v[50:53]
	v_mfma_f32_16x16x32_bf16 v[50:53], v[206:209], v[214:217], v[50:53]
	v_mfma_f32_16x16x32_bf16 v[38:41], v[170:173], v[218:221], v[38:41]
	v_mfma_f32_16x16x32_bf16 v[38:41], v[174:177], v[222:225], v[38:41]
	v_mfma_f32_16x16x32_bf16 v[34:37], v[202:205], v[218:221], v[34:37]
	v_mfma_f32_16x16x32_bf16 v[34:37], v[206:209], v[222:225], v[34:37]
	v_mfma_f32_16x16x32_bf16 v[22:25], v[170:173], v[226:229], v[22:25]
	v_mfma_f32_16x16x32_bf16 v[22:25], v[174:177], v[230:233], v[22:25]
	v_mfma_f32_16x16x32_bf16 v[18:21], v[202:205], v[226:229], v[18:21]
	v_mfma_f32_16x16x32_bf16 v[18:21], v[206:209], v[230:233], v[18:21]
	v_mfma_f32_16x16x32_bf16 v[6:9], v[170:173], v[234:237], v[6:9]
	v_mfma_f32_16x16x32_bf16 v[6:9], v[174:177], v[238:241], v[6:9]
	v_mfma_f32_16x16x32_bf16 v[2:5], v[202:205], v[234:237], v[2:5]
	v_mfma_f32_16x16x32_bf16 v[2:5], v[206:209], v[238:241], v[2:5]
	s_barrier
	s_setprio 0
	s_add_u32 s12, s12, 0x100
	s_addc_u32 s13, s13, 0
	s_add_u32 s16, s16, 0x100
	s_addc_u32 s17, s17, 0
	s_cmp_ge_u32 s42, s28
	s_mov_b32 s14, s42
	s_cbranch_scc0 .LBB0_322
	s_branch .Lk_done
.LBB0_322:
	s_add_i32 s42, s14, 2
	s_add_u32 s43, s12, 0x80
	s_addc_u32 s15, s13, 0
	s_add_i32 s75, 0, 0x10000
	s_cmp_eq_u32 s25, s14
	s_cselect_b32 s15, s55, s15
	s_cselect_b32 s14, s54, s43
	s_cselect_b32 vcc_hi, s65, s17
	s_cselect_b32 vcc_lo, s64, s16
	s_add_i32 s43, 0, 0x14000
	v_add_u32_e32 v142, s75, v199
	v_add_u32_e32 v178, s43, v199
	ds_read_b128 v[130:133], v142
	ds_read_b128 v[134:137], v142 offset:1024
	ds_read_b128 v[138:141], v142 offset:2048
	ds_read_b128 v[142:145], v142 offset:3072
	ds_read_b128 v[170:173], v178
	ds_read_b128 v[174:177], v178 offset:1024
	ds_read_b128 v[202:205], v178 offset:2048
	ds_read_b128 v[206:209], v178 offset:3072
	v_lshl_add_u64 v[178:179], s[12:13], 0, v[166:167]
	s_add_i32 m0, s56, 0xc000
	ds_read_b128 v[210:213], v201
	ds_read_b128 v[214:217], v201 offset:1024
	ds_read_b128 v[218:221], v201 offset:2048
	ds_read_b128 v[222:225], v201 offset:3072
	ds_read_b128 v[226:229], v201 offset:4096
	ds_read_b128 v[230:233], v201 offset:5120
	ds_read_b128 v[234:237], v201 offset:6144
	ds_read_b128 v[238:241], v201 offset:7168
	global_load_lds_dwordx4 v[178:179], off
	v_lshl_add_u64 v[178:179], s[12:13], 0, v[168:169]
	s_add_i32 m0, s56, 0xe000
	s_nop 0
	global_load_lds_dwordx4 v[178:179], off
	s_waitcnt vmcnt(8)
	s_waitcnt lgkmcnt(0)
	s_setprio 1
	s_barrier
; #define PG8_STAGE(bufoff, gbase, voff) do { _Pragma("unroll") for (int _i = 0; _i < 2; ++_i) \
;         __builtin_amdgcn_global_load_lds((const unsigned*)((const char*)(gbase) + (voff)[_i]), (PG8_LAS unsigned*)(lds + (bufoff) + ldsw + _i * 8192), 16, 0, 0); } while (0)
; #define PG8_LDA(dst, b, h) do { _Pragma("unroll") for (int m = 0; m < 4; ++m) _Pragma("unroll") for (int k = 0; k < 2; ++k) dst[m][k] = *(const PG8_LAS bf16x8*)(lds + PG8_SA(b, h) + aoff + m * 2048 + k * 1024); } while (0)
; #define PG8_LDB(dst, b, h) do { _Pragma("unroll") for (int n = 0; n < 2; ++n) _Pragma("unroll") for (int k = 0; k < 2; ++k) dst[n][k] = *(const PG8_LAS bf16x8*)(lds + PG8_SB(b, h) + boff + n * 2048 + k * 1024); } while (0)
; #define PG8_MMA(ai, bj, At, Bt) do { __builtin_amdgcn_s_setprio(1); _Pragma("unroll") for (int m = 0; m < 4; ++m) _Pragma("unroll") for (int n = 0; n < 2; ++n) _Pragma("unroll") for (int k = 0; k < 2; ++k) \
;         acc[ai][bj][m][n] = __builtin_amdgcn_mfma_f32_16x16x32_bf16(Bt[n][k], At[m][k], acc[ai][bj][m][n], 0, 0, 0); __builtin_amdgcn_s_setprio(0); } while (0)
; #define PG8_WAIT_V(n) asm volatile("s_waitcnt vmcnt(" #n ")" ::: "memory")
; #define PG8_WAIT_L(n) asm volatile("s_waitcnt lgkmcnt(" #n ")" ::: "memory")
; #define PG8_BAR __builtin_amdgcn_s_barrier()
; #define PG8_SCHED __builtin_amdgcn_sched_barrier(0)
; template <class Epi, class Sched, bool ALIGN_EPI = false, bool SP2 = false>
; __device__ __forceinline__ void gemm_phase(PG8_LAS unsigned char* lds, const Gemm g, const Sched& S, const Epi& E) {
;     ...
;             PG8_LDB(B0, 0, 0); PG8_LDB(B1, 0, 1); PG8_SCHED; PG8_LDA(At, 0, 0); PG8_STAGE(PG8_SA(1, 1), a1 + hstep, voffA);
;             PG8_WAIT_V(8); PG8_WAIT_L(0); PG8_BAR; PG8_MMA(0, 0, At, B0); PG8_MMA(0, 1, At, B1); PG8_BAR; PG8_SCHED;
;             PG8_LDA(At, 0, 1); PG8_STAGE(PG8_SB(0, 0), b2, voffB); PG8_STAGE(PG8_SB(0, 1), b2 + hstep, voffB); PG8_STAGE(PG8_SA(0, 0), a2, voffA);
;             PG8_WAIT_V(8); PG8_WAIT_L(0); PG8_BAR; PG8_MMA(1, 0, At, B0); PG8_MMA(1, 1, At, B1); PG8_BAR; PG8_SCHED;
	v_mfma_f32_16x16x32_bf16 v[126:129], v[130:133], v[210:213], v[126:129]
	v_mfma_f32_16x16x32_bf16 v[126:129], v[134:137], v[214:217], v[126:129]
	v_mfma_f32_16x16x32_bf16 v[122:125], v[138:141], v[210:213], v[122:125]
	v_mfma_f32_16x16x32_bf16 v[122:125], v[142:145], v[214:217], v[122:125]
	v_mfma_f32_16x16x32_bf16 v[110:113], v[130:133], v[218:221], v[110:113]
	v_mfma_f32_16x16x32_bf16 v[110:113], v[134:137], v[222:225], v[110:113]
	v_mfma_f32_16x16x32_bf16 v[106:109], v[138:141], v[218:221], v[106:109]
	v_mfma_f32_16x16x32_bf16 v[106:109], v[142:145], v[222:225], v[106:109]
	v_mfma_f32_16x16x32_bf16 v[94:97], v[130:133], v[226:229], v[94:97]
	v_mfma_f32_16x16x32_bf16 v[94:97], v[134:137], v[230:233], v[94:97]
	v_mfma_f32_16x16x32_bf16 v[90:93], v[138:141], v[226:229], v[90:93]
	v_mfma_f32_16x16x32_bf16 v[90:93], v[142:145], v[230:233], v[90:93]
	v_mfma_f32_16x16x32_bf16 v[78:81], v[130:133], v[234:237], v[78:81]
	v_mfma_f32_16x16x32_bf16 v[78:81], v[134:137], v[238:241], v[78:81]
	v_mfma_f32_16x16x32_bf16 v[74:77], v[138:141], v[234:237], v[74:77]
	v_mfma_f32_16x16x32_bf16 v[74:77], v[142:145], v[238:241], v[74:77]
	v_mfma_f32_16x16x32_bf16 v[118:121], v[170:173], v[210:213], v[118:121]
	v_mfma_f32_16x16x32_bf16 v[118:121], v[174:177], v[214:217], v[118:121]
	v_mfma_f32_16x16x32_bf16 v[114:117], v[202:205], v[210:213], v[114:117]
	v_mfma_f32_16x16x32_bf16 v[114:117], v[206:209], v[214:217], v[114:117]
	v_mfma_f32_16x16x32_bf16 v[102:105], v[170:173], v[218:221], v[102:105]
	v_mfma_f32_16x16x32_bf16 v[102:105], v[174:177], v[222:225], v[102:105]
	v_mfma_f32_16x16x32_bf16 v[98:101], v[202:205], v[218:221], v[98:101]
	v_mfma_f32_16x16x32_bf16 v[98:101], v[206:209], v[222:225], v[98:101]
	v_mfma_f32_16x16x32_bf16 v[86:89], v[170:173], v[226:229], v[86:89]
	v_mfma_f32_16x16x32_bf16 v[86:89], v[174:177], v[230:233], v[86:89]
	v_mfma_f32_16x16x32_bf16 v[82:85], v[202:205], v[226:229], v[82:85]
	v_mfma_f32_16x16x32_bf16 v[82:85], v[206:209], v[230:233], v[82:85]
	v_mfma_f32_16x16x32_bf16 v[70:73], v[170:173], v[234:237], v[70:73]
	v_mfma_f32_16x16x32_bf16 v[70:73], v[174:177], v[238:241], v[70:73]
	v_mfma_f32_16x16x32_bf16 v[66:69], v[202:205], v[234:237], v[66:69]
	v_mfma_f32_16x16x32_bf16 v[66:69], v[206:209], v[238:241], v[66:69]
	s_barrier
	s_setprio 0
	s_add_i32 s75, s75, s23
	v_lshl_add_u64 v[178:179], vcc, 0, v[0:1]
	s_mov_b32 m0, s75
	ds_read_b128 v[210:213], v201 offset:16384
	ds_read_b128 v[214:217], v201 offset:17408
	ds_read_b128 v[218:221], v201 offset:18432
	ds_read_b128 v[222:225], v201 offset:19456
	ds_read_b128 v[226:229], v201 offset:20480
	ds_read_b128 v[230:233], v201 offset:21504
	ds_read_b128 v[234:237], v201 offset:22528
	ds_read_b128 v[238:241], v201 offset:23552
	global_load_lds_dwordx4 v[178:179], off
	s_add_i32 m0, s75, 0x2000
	v_lshl_add_u64 v[242:243], vcc, 0, v[162:163]
	s_add_u32 vcc_lo, vcc_lo, s84
	s_addc_u32 vcc_hi, vcc_hi, 0
	s_add_i32 s43, s43, s23
	global_load_lds_dwordx4 v[242:243], off
	v_lshl_add_u64 v[244:245], vcc, 0, v[0:1]
	s_mov_b32 m0, s43
	v_lshl_add_u64 v[246:247], vcc, 0, v[162:163]
	global_load_lds_dwordx4 v[244:245], off
	s_add_i32 m0, s43, 0x2000
	v_lshl_add_u64 v[248:249], s[14:15], 0, v[158:159]
	global_load_lds_dwordx4 v[246:247], off
	s_mov_b32 m0, s56
	v_lshl_add_u64 v[250:251], s[14:15], 0, v[160:161]
	global_load_lds_dwordx4 v[248:249], off
	s_mov_b32 m0, s82
	s_nop 0
	global_load_lds_dwordx4 v[250:251], off
	s_waitcnt vmcnt(8)
	s_waitcnt lgkmcnt(0)
	s_setprio 1
	s_barrier
	v_mfma_f32_16x16x32_bf16 v[62:65], v[130:133], v[210:213], v[62:65]
	v_mfma_f32_16x16x32_bf16 v[62:65], v[134:137], v[214:217], v[62:65]
	v_mfma_f32_16x16x32_bf16 v[58:61], v[138:141], v[210:213], v[58:61]
	v_mfma_f32_16x16x32_bf16 v[58:61], v[142:145], v[214:217], v[58:61]
	v_mfma_f32_16x16x32_bf16 v[46:49], v[130:133], v[218:221], v[46:49]
	v_mfma_f32_16x16x32_bf16 v[46:49], v[134:137], v[222:225], v[46:49]
	v_mfma_f32_16x16x32_bf16 v[42:45], v[138:141], v[218:221], v[42:45]
	v_mfma_f32_16x16x32_bf16 v[42:45], v[142:145], v[222:225], v[42:45]
	v_mfma_f32_16x16x32_bf16 v[30:33], v[130:133], v[226:229], v[30:33]
	v_mfma_f32_16x16x32_bf16 v[30:33], v[134:137], v[230:233], v[30:33]
	v_mfma_f32_16x16x32_bf16 v[26:29], v[138:141], v[226:229], v[26:29]
	v_mfma_f32_16x16x32_bf16 v[26:29], v[142:145], v[230:233], v[26:29]
	v_mfma_f32_16x16x32_bf16 v[14:17], v[130:133], v[234:237], v[14:17]
	v_mfma_f32_16x16x32_bf16 v[14:17], v[134:137], v[238:241], v[14:17]
	v_mfma_f32_16x16x32_bf16 v[10:13], v[138:141], v[234:237], v[10:13]
	v_mfma_f32_16x16x32_bf16 v[10:13], v[142:145], v[238:241], v[10:13]
	v_mfma_f32_16x16x32_bf16 v[54:57], v[170:173], v[210:213], v[54:57]
	v_mfma_f32_16x16x32_bf16 v[54:57], v[174:177], v[214:217], v[54:57]
	v_mfma_f32_16x16x32_bf16 v[50:53], v[202:205], v[210:213], v[50:53]
	v_mfma_f32_16x16x32_bf16 v[50:53], v[206:209], v[214:217], v[50:53]
	v_mfma_f32_16x16x32_bf16 v[38:41], v[170:173], v[218:221], v[38:41]
	v_mfma_f32_16x16x32_bf16 v[38:41], v[174:177], v[222:225], v[38:41]
	v_mfma_f32_16x16x32_bf16 v[34:37], v[202:205], v[218:221], v[34:37]
	v_mfma_f32_16x16x32_bf16 v[34:37], v[206:209], v[222:225], v[34:37]
	v_mfma_f32_16x16x32_bf16 v[22:25], v[170:173], v[226:229], v[22:25]
	v_mfma_f32_16x16x32_bf16 v[22:25], v[174:177], v[230:233], v[22:25]
	v_mfma_f32_16x16x32_bf16 v[18:21], v[202:205], v[226:229], v[18:21]
	v_mfma_f32_16x16x32_bf16 v[18:21], v[206:209], v[230:233], v[18:21]
	v_mfma_f32_16x16x32_bf16 v[6:9], v[170:173], v[234:237], v[6:9]
	v_mfma_f32_16x16x32_bf16 v[6:9], v[174:177], v[238:241], v[6:9]
	v_mfma_f32_16x16x32_bf16 v[2:5], v[202:205], v[234:237], v[2:5]
	v_mfma_f32_16x16x32_bf16 v[2:5], v[206:209], v[238:241], v[2:5]
	s_barrier
; #define PG8_STAGE(bufoff, gbase, voff) do { _Pragma("unroll") for (int _i = 0; _i < 2; ++_i) \
;         __builtin_amdgcn_global_load_lds((const unsigned*)((const char*)(gbase) + (voff)[_i]), (PG8_LAS unsigned*)(lds + (bufoff) + ldsw + _i * 8192), 16, 0, 0); } while (0)
; #define PG8_LDA(dst, b, h) do { _Pragma("unroll") for (int m = 0; m < 4; ++m) _Pragma("unroll") for (int k = 0; k < 2; ++k) dst[m][k] = *(const PG8_LAS bf16x8*)(lds + PG8_SA(b, h) + aoff + m * 2048 + k * 1024); } while (0)
; #define PG8_LDB(dst, b, h) do { _Pragma("unroll") for (int n = 0; n < 2; ++n) _Pragma("unroll") for (int k = 0; k < 2; ++k) dst[n][k] = *(const PG8_LAS bf16x8*)(lds + PG8_SB(b, h) + boff + n * 2048 + k * 1024); } while (0)
; #define PG8_MMA(ai, bj, At, Bt) do { __builtin_amdgcn_s_setprio(1); _Pragma("unroll") for (int m = 0; m < 4; ++m) _Pragma("unroll") for (int n = 0; n < 2; ++n) _Pragma("unroll") for (int k = 0; k < 2; ++k) \
;         acc[ai][bj][m][n] = __builtin_amdgcn_mfma_f32_16x16x32_bf16(Bt[n][k], At[m][k], acc[ai][bj][m][n], 0, 0, 0); __builtin_amdgcn_s_setprio(0); } while (0)
; #define PG8_WAIT_V(n) asm volatile("s_waitcnt vmcnt(" #n ")" ::: "memory")
; #define PG8_WAIT_L(n) asm volatile("s_waitcnt lgkmcnt(" #n ")" ::: "memory")
; #define PG8_BAR __builtin_amdgcn_s_barrier()
; #define PG8_SCHED __builtin_amdgcn_sched_barrier(0)
; template <class Epi, class Sched, bool ALIGN_EPI = false, bool SP2 = false>
; __device__ __forceinline__ void gemm_phase(PG8_LAS unsigned char* lds, const Gemm g, const Sched& S, const Epi& E) {
;     ...
;             PG8_LDB(B0, 1, 0); PG8_LDB(B1, 1, 1); PG8_SCHED; PG8_LDA(At, 1, 0); PG8_STAGE(PG8_SA(0, 1), a2 + hstep, voffA);
;             PG8_WAIT_V(8); PG8_WAIT_L(0); PG8_BAR; PG8_MMA(0, 0, At, B0); PG8_MMA(0, 1, At, B1); PG8_BAR; PG8_SCHED;
;             PG8_LDA(At, 1, 1); PG8_STAGE(PG8_SB(1, 0), b3, voffB); PG8_STAGE(PG8_SB(1, 1), b3 + hstep, voffB); PG8_STAGE(PG8_SA(1, 0), a3, voffA);
;             PG8_WAIT_V(8); PG8_WAIT_L(0); PG8_BAR; PG8_MMA(1, 0, At, B0); PG8_MMA(1, 1, At, B1); PG8_BAR; PG8_SCHED;
	s_setprio 0
	s_add_i32 s43, 0, 0x18000
	s_add_i32 s75, 0, 0x1c000
	v_add_u32_e32 v142, s43, v199
	v_add_u32_e32 v206, s75, v199
	ds_read_b128 v[130:133], v142
	ds_read_b128 v[134:137], v142 offset:1024
	ds_read_b128 v[138:141], v142 offset:2048
	ds_read_b128 v[142:145], v142 offset:3072
	ds_read_b128 v[170:173], v206
	ds_read_b128 v[174:177], v206 offset:1024
	ds_read_b128 v[202:205], v206 offset:2048
	ds_read_b128 v[206:209], v206 offset:3072
	s_add_u32 s14, s14, s84
	s_addc_u32 s15, s15, 0
	s_mov_b32 m0, s83
	v_lshl_add_u64 v[252:253], s[14:15], 0, v[158:159]
	ds_read_b128 v[210:213], v201 offset:32768
	ds_read_b128 v[214:217], v201 offset:33792
	ds_read_b128 v[218:221], v201 offset:34816
	ds_read_b128 v[222:225], v201 offset:35840
	ds_read_b128 v[226:229], v201 offset:36864
	ds_read_b128 v[230:233], v201 offset:37888
	ds_read_b128 v[234:237], v201 offset:38912
	ds_read_b128 v[238:241], v201 offset:39936
	global_load_lds_dwordx4 v[252:253], off
	v_lshl_add_u64 v[252:253], s[14:15], 0, v[160:161]
	s_mov_b32 m0, s24
	s_nop 0
	global_load_lds_dwordx4 v[252:253], off
	s_waitcnt vmcnt(8)
	s_waitcnt lgkmcnt(0)
	s_setprio 1
	s_barrier
	v_mfma_f32_16x16x32_bf16 v[126:129], v[130:133], v[210:213], v[126:129]
	v_mfma_f32_16x16x32_bf16 v[126:129], v[134:137], v[214:217], v[126:129]
	v_mfma_f32_16x16x32_bf16 v[122:125], v[138:141], v[210:213], v[122:125]
	v_mfma_f32_16x16x32_bf16 v[122:125], v[142:145], v[214:217], v[122:125]
	v_mfma_f32_16x16x32_bf16 v[110:113], v[130:133], v[218:221], v[110:113]
	v_mfma_f32_16x16x32_bf16 v[110:113], v[134:137], v[222:225], v[110:113]
	v_mfma_f32_16x16x32_bf16 v[106:109], v[138:141], v[218:221], v[106:109]
	v_mfma_f32_16x16x32_bf16 v[106:109], v[142:145], v[222:225], v[106:109]
	v_mfma_f32_16x16x32_bf16 v[94:97], v[130:133], v[226:229], v[94:97]
	v_mfma_f32_16x16x32_bf16 v[94:97], v[134:137], v[230:233], v[94:97]
	v_mfma_f32_16x16x32_bf16 v[90:93], v[138:141], v[226:229], v[90:93]
	v_mfma_f32_16x16x32_bf16 v[90:93], v[142:145], v[230:233], v[90:93]
	v_mfma_f32_16x16x32_bf16 v[78:81], v[130:133], v[234:237], v[78:81]
	v_mfma_f32_16x16x32_bf16 v[78:81], v[134:137], v[238:241], v[78:81]
	v_mfma_f32_16x16x32_bf16 v[74:77], v[138:141], v[234:237], v[74:77]
	v_mfma_f32_16x16x32_bf16 v[74:77], v[142:145], v[238:241], v[74:77]
	v_mfma_f32_16x16x32_bf16 v[118:121], v[170:173], v[210:213], v[118:121]
	v_mfma_f32_16x16x32_bf16 v[118:121], v[174:177], v[214:217], v[118:121]
	v_mfma_f32_16x16x32_bf16 v[114:117], v[202:205], v[210:213], v[114:117]
	v_mfma_f32_16x16x32_bf16 v[114:117], v[206:209], v[214:217], v[114:117]
	v_mfma_f32_16x16x32_bf16 v[102:105], v[170:173], v[218:221], v[102:105]
	v_mfma_f32_16x16x32_bf16 v[102:105], v[174:177], v[222:225], v[102:105]
	v_mfma_f32_16x16x32_bf16 v[98:101], v[202:205], v[218:221], v[98:101]
	v_mfma_f32_16x16x32_bf16 v[98:101], v[206:209], v[222:225], v[98:101]
	v_mfma_f32_16x16x32_bf16 v[86:89], v[170:173], v[226:229], v[86:89]
	v_mfma_f32_16x16x32_bf16 v[86:89], v[174:177], v[230:233], v[86:89]
	v_mfma_f32_16x16x32_bf16 v[82:85], v[202:205], v[226:229], v[82:85]
	v_mfma_f32_16x16x32_bf16 v[82:85], v[206:209], v[230:233], v[82:85]
	v_mfma_f32_16x16x32_bf16 v[70:73], v[170:173], v[234:237], v[70:73]
	v_mfma_f32_16x16x32_bf16 v[70:73], v[174:177], v[238:241], v[70:73]
	v_mfma_f32_16x16x32_bf16 v[66:69], v[202:205], v[234:237], v[66:69]
	v_mfma_f32_16x16x32_bf16 v[66:69], v[206:209], v[238:241], v[66:69]
	s_barrier
	s_setprio 0
	s_add_i32 s14, s43, s23
	v_lshl_add_u64 v[178:179], v[178:179], 0, s[94:95]
	s_mov_b32 m0, s14
	ds_read_b128 v[210:213], v201 offset:49152
	ds_read_b128 v[214:217], v201 offset:50176
	ds_read_b128 v[218:221], v201 offset:51200
	ds_read_b128 v[222:225], v201 offset:52224
	ds_read_b128 v[226:229], v201 offset:53248
	ds_read_b128 v[230:233], v201 offset:54272
	ds_read_b128 v[234:237], v201 offset:55296
	ds_read_b128 v[238:241], v201 offset:56320
	global_load_lds_dwordx4 v[178:179], off
	v_lshl_add_u64 v[178:179], v[242:243], 0, s[94:95]
	s_add_i32 m0, s14, 0x2000
	s_add_i32 s14, s75, s23
	global_load_lds_dwordx4 v[178:179], off
	v_lshl_add_u64 v[178:179], v[244:245], 0, s[94:95]
	s_mov_b32 m0, s14
	s_nop 0
	global_load_lds_dwordx4 v[178:179], off
	v_lshl_add_u64 v[178:179], v[246:247], 0, s[94:95]
	s_add_i32 m0, s14, 0x2000
	s_nop 0
	global_load_lds_dwordx4 v[178:179], off
	v_lshl_add_u64 v[178:179], v[248:249], 0, s[94:95]
	s_mov_b32 m0, s63
	s_nop 0
	global_load_lds_dwordx4 v[178:179], off
	v_lshl_add_u64 v[178:179], v[250:251], 0, s[94:95]
	s_mov_b32 m0, s70
	s_nop 0
	global_load_lds_dwordx4 v[178:179], off
	s_waitcnt vmcnt(8)
	s_waitcnt lgkmcnt(0)
	s_setprio 1
	s_barrier
	v_mfma_f32_16x16x32_bf16 v[62:65], v[130:133], v[210:213], v[62:65]
	v_mfma_f32_16x16x32_bf16 v[62:65], v[134:137], v[214:217], v[62:65]
	v_mfma_f32_16x16x32_bf16 v[58:61], v[138:141], v[210:213], v[58:61]
	v_mfma_f32_16x16x32_bf16 v[58:61], v[142:145], v[214:217], v[58:61]
	v_mfma_f32_16x16x32_bf16 v[46:49], v[130:133], v[218:221], v[46:49]
	v_mfma_f32_16x16x32_bf16 v[46:49], v[134:137], v[222:225], v[46:49]
	v_mfma_f32_16x16x32_bf16 v[42:45], v[138:141], v[218:221], v[42:45]
	v_mfma_f32_16x16x32_bf16 v[42:45], v[142:145], v[222:225], v[42:45]
	v_mfma_f32_16x16x32_bf16 v[30:33], v[130:133], v[226:229], v[30:33]
	v_mfma_f32_16x16x32_bf16 v[30:33], v[134:137], v[230:233], v[30:33]
	v_mfma_f32_16x16x32_bf16 v[26:29], v[138:141], v[226:229], v[26:29]
	v_mfma_f32_16x16x32_bf16 v[26:29], v[142:145], v[230:233], v[26:29]
	v_mfma_f32_16x16x32_bf16 v[14:17], v[130:133], v[234:237], v[14:17]
	v_mfma_f32_16x16x32_bf16 v[14:17], v[134:137], v[238:241], v[14:17]
	v_mfma_f32_16x16x32_bf16 v[10:13], v[138:141], v[234:237], v[10:13]
	v_mfma_f32_16x16x32_bf16 v[10:13], v[142:145], v[238:241], v[10:13]
	v_mfma_f32_16x16x32_bf16 v[54:57], v[170:173], v[210:213], v[54:57]
	v_mfma_f32_16x16x32_bf16 v[54:57], v[174:177], v[214:217], v[54:57]
	v_mfma_f32_16x16x32_bf16 v[50:53], v[202:205], v[210:213], v[50:53]
	v_mfma_f32_16x16x32_bf16 v[50:53], v[206:209], v[214:217], v[50:53]
	v_mfma_f32_16x16x32_bf16 v[38:41], v[170:173], v[218:221], v[38:41]
	v_mfma_f32_16x16x32_bf16 v[38:41], v[174:177], v[222:225], v[38:41]
	v_mfma_f32_16x16x32_bf16 v[34:37], v[202:205], v[218:221], v[34:37]
	v_mfma_f32_16x16x32_bf16 v[34:37], v[206:209], v[222:225], v[34:37]
	v_mfma_f32_16x16x32_bf16 v[22:25], v[170:173], v[226:229], v[22:25]
	v_mfma_f32_16x16x32_bf16 v[22:25], v[174:177], v[230:233], v[22:25]
	v_mfma_f32_16x16x32_bf16 v[18:21], v[202:205], v[226:229], v[18:21]
	v_mfma_f32_16x16x32_bf16 v[18:21], v[206:209], v[230:233], v[18:21]
	v_mfma_f32_16x16x32_bf16 v[6:9], v[170:173], v[234:237], v[6:9]
	v_mfma_f32_16x16x32_bf16 v[6:9], v[174:177], v[238:241], v[6:9]
	v_mfma_f32_16x16x32_bf16 v[2:5], v[202:205], v[234:237], v[2:5]
	v_mfma_f32_16x16x32_bf16 v[2:5], v[206:209], v[238:241], v[2:5]
	s_barrier
	s_setprio 0
	s_add_u32 s12, s12, 0x100
	s_addc_u32 s13, s13, 0
	s_add_u32 s16, s16, 0x100
	s_addc_u32 s17, s17, 0
	s_cmp_ge_u32 s42, s28
	s_mov_b32 s14, s42
	s_cbranch_scc0 .LBB0_322
